# peel+tr1d+slab5 stack plus P5 scalar table: the load pairs of chunk blocks 2..4 hoisted behind block 1's, counted vmcnt per block
# baseline (speedup 1.0000x reference)
; __device__ __forceinline__ void mlstm_scalar_table_wg(Frame& F, int bh) {
;     ...
;     for (int i = 0; i < 4; ++i) { const int c = 4 * wave + i; const size_t r = (size_t)b * SEQ + (size_t)c * 64 + lane;
;         const float ig = GT[r * 8 + h], lf = GT[r * 8 + 4 + h];
;         float s = lf;
; #pragma unroll
;         for (int o = 1; o < 64; o <<= 1) { const float t = __shfl_up(s, o); if (lane >= o) s += t; }
;         bc[i] = s; as[i] = ig - s; float p = as[i];
; #pragma unroll
;         for (int o = 1; o < 64; o <<= 1) { const float t = __shfl_up(p, o); if (lane >= o) p = fmaxf(p, t); }
;         pm[i] = p;
;         if (lane == 63) { B63[c] = s; P63[c] = p; } }
.LBB0_691:
	s_ashr_i32 s30, s26, 2
	s_and_b32 s27, s26, 3
	s_ashr_i32 s31, s30, 31
	s_lshl_b32 s27, s27, 2
	s_add_u32 s27, s3, s27
	s_addc_u32 s28, s24, 0
	s_lshl_b64 s[60:61], s[30:31], 16
	s_add_u32 s29, s27, s20
	s_addc_u32 s31, s28, s21
	s_add_u32 s30, s29, s60
	s_addc_u32 s31, s31, s61
	v_lshl_add_u64 v[4:5], s[30:31], 0, v[10:11]
	global_load_dword v3, v[4:5], off offset:16
	s_nop 0
	global_load_dword v4, v[4:5], off
	s_add_u32 s72, s27, s22
	s_addc_u32 s73, s28, s23
	s_add_u32 s72, s72, s60
	s_addc_u32 s73, s73, s61
	s_nop 0
	v_lshl_add_u64 v[206:207], s[72:73], 0, v[10:11]
	global_load_dword v200, v[206:207], off offset:16
	global_load_dword v201, v[206:207], off
	s_add_u32 s72, s27, s38
	s_addc_u32 s73, s28, s39
	s_add_u32 s72, s72, s60
	s_addc_u32 s73, s73, s61
	s_nop 0
	v_lshl_add_u64 v[206:207], s[72:73], 0, v[10:11]
	global_load_dword v202, v[206:207], off offset:16
	global_load_dword v203, v[206:207], off
	s_add_u32 s72, s27, s40
	s_addc_u32 s73, s28, s41
	s_add_u32 s72, s72, s60
	s_addc_u32 s73, s73, s61
	s_nop 0
	v_lshl_add_u64 v[206:207], s[72:73], 0, v[10:11]
	global_load_dword v204, v[206:207], off offset:16
	global_load_dword v205, v[206:207], off
	s_waitcnt vmcnt(6)
	ds_bpermute_b32 v5, v18, v3
	s_waitcnt lgkmcnt(0)
	v_add_f32_e32 v5, v3, v5
	v_cndmask_b32_e64 v3, v5, v3, s[18:19]
	ds_bpermute_b32 v5, v19, v3
	s_waitcnt lgkmcnt(0)
	v_add_f32_e32 v5, v3, v5
	v_cndmask_b32_e64 v3, v5, v3, s[6:7]
	ds_bpermute_b32 v5, v20, v3
	s_waitcnt lgkmcnt(0)
	v_add_f32_e32 v5, v3, v5
	v_cndmask_b32_e64 v3, v5, v3, s[8:9]
	ds_bpermute_b32 v5, v21, v3
	s_waitcnt lgkmcnt(0)
	v_add_f32_e32 v5, v3, v5
	v_cndmask_b32_e64 v3, v5, v3, s[10:11]
	ds_bpermute_b32 v5, v22, v3
	s_waitcnt lgkmcnt(0)
	v_add_f32_e32 v5, v3, v5
	v_cndmask_b32_e64 v5, v5, v3, s[12:13]
	ds_bpermute_b32 v3, v23, v5
	s_waitcnt lgkmcnt(0)
	v_add_f32_e32 v3, v5, v3
	v_cndmask_b32_e64 v35, v3, v5, s[14:15]
	v_sub_f32_e32 v33, v4, v35
	ds_bpermute_b32 v4, v18, v33
	s_waitcnt lgkmcnt(0)
	v_max_f32_e32 v4, v4, v4
	v_max_f32_e32 v4, v33, v4
	v_cndmask_b32_e64 v4, v4, v33, s[18:19]
	ds_bpermute_b32 v5, v19, v4
	s_waitcnt lgkmcnt(0)
	v_max_f32_e32 v5, v5, v5
	v_max_f32_e32 v5, v4, v5
	v_cndmask_b32_e64 v4, v5, v4, s[6:7]
	ds_bpermute_b32 v5, v20, v4
	s_waitcnt lgkmcnt(0)
	v_max_f32_e32 v5, v5, v5
	v_max_f32_e32 v5, v4, v5
	v_cndmask_b32_e64 v4, v5, v4, s[8:9]
	ds_bpermute_b32 v5, v21, v4
	s_waitcnt lgkmcnt(0)
	v_max_f32_e32 v5, v5, v5
	v_max_f32_e32 v5, v4, v5
	v_cndmask_b32_e64 v4, v5, v4, s[10:11]
	ds_bpermute_b32 v5, v22, v4
	s_waitcnt lgkmcnt(0)
	v_max_f32_e32 v5, v5, v5
	v_max_f32_e32 v5, v4, v5
	v_cndmask_b32_e64 v39, v5, v4, s[12:13]
	ds_bpermute_b32 v4, v23, v39
	v_max_f32_e32 v5, v39, v39
	s_waitcnt lgkmcnt(0)
	v_max_f32_e32 v4, v4, v4
	v_max_f32_e32 v40, v5, v4
	s_and_saveexec_b64 s[62:63], s[0:1]
	v_mov_b32_e32 v4, s25
	ds_write2_b32 v4, v3, v40 offset1:32
	s_or_b64 exec, exec, s[62:63]
	s_add_u32 s29, s27, s22
	s_addc_u32 s31, s28, s23
	s_add_u32 s30, s29, s60
	s_addc_u32 s31, s31, s61
	v_lshl_add_u64 v[4:5], s[30:31], 0, v[10:11]
	s_waitcnt vmcnt(4)
	v_mov_b32_e32 v3, v200
	v_mov_b32_e32 v4, v201
	ds_bpermute_b32 v5, v18, v3
	s_waitcnt lgkmcnt(0)
	v_add_f32_e32 v5, v3, v5
	v_cndmask_b32_e64 v3, v5, v3, s[18:19]
	ds_bpermute_b32 v5, v19, v3
	s_waitcnt lgkmcnt(0)
	v_add_f32_e32 v5, v3, v5
	v_cndmask_b32_e64 v3, v5, v3, s[6:7]
	ds_bpermute_b32 v5, v20, v3
	s_waitcnt lgkmcnt(0)
	v_add_f32_e32 v5, v3, v5
	v_cndmask_b32_e64 v3, v5, v3, s[8:9]
	ds_bpermute_b32 v5, v21, v3
	s_waitcnt lgkmcnt(0)
	v_add_f32_e32 v5, v3, v5
	v_cndmask_b32_e64 v3, v5, v3, s[10:11]
	ds_bpermute_b32 v5, v22, v3
	s_waitcnt lgkmcnt(0)
	v_add_f32_e32 v5, v3, v5
	v_cndmask_b32_e64 v5, v5, v3, s[12:13]
	ds_bpermute_b32 v3, v23, v5
	s_waitcnt lgkmcnt(0)
	v_add_f32_e32 v3, v5, v3
	v_cndmask_b32_e64 v32, v3, v5, s[14:15]
	v_sub_f32_e32 v31, v4, v32
	ds_bpermute_b32 v4, v18, v31
	s_waitcnt lgkmcnt(0)
	v_max_f32_e32 v4, v4, v4
	v_max_f32_e32 v4, v31, v4
	v_cndmask_b32_e64 v4, v4, v31, s[18:19]
	ds_bpermute_b32 v5, v19, v4
	s_waitcnt lgkmcnt(0)
	v_max_f32_e32 v5, v5, v5
	v_max_f32_e32 v5, v4, v5
	v_cndmask_b32_e64 v4, v5, v4, s[6:7]
	ds_bpermute_b32 v5, v20, v4
	s_waitcnt lgkmcnt(0)
	v_max_f32_e32 v5, v5, v5
	v_max_f32_e32 v5, v4, v5
	v_cndmask_b32_e64 v4, v5, v4, s[8:9]
	ds_bpermute_b32 v5, v21, v4
	s_waitcnt lgkmcnt(0)
	v_max_f32_e32 v5, v5, v5
	v_max_f32_e32 v5, v4, v5
	v_cndmask_b32_e64 v4, v5, v4, s[10:11]
	ds_bpermute_b32 v5, v22, v4
	s_waitcnt lgkmcnt(0)
	v_max_f32_e32 v5, v5, v5
	v_max_f32_e32 v5, v4, v5
	v_cndmask_b32_e64 v37, v5, v4, s[12:13]
	ds_bpermute_b32 v4, v23, v37
	v_max_f32_e32 v5, v37, v37
	s_waitcnt lgkmcnt(0)
	v_max_f32_e32 v4, v4, v4
	v_max_f32_e32 v38, v5, v4
	s_and_saveexec_b64 s[62:63], s[0:1]
	v_mov_b32_e32 v4, s25
	ds_write2_b32 v4, v3, v38 offset0:1 offset1:33
	s_or_b64 exec, exec, s[62:63]
	s_add_u32 s29, s27, s38
	s_addc_u32 s31, s28, s39
	s_add_u32 s30, s29, s60
	s_addc_u32 s31, s31, s61
	v_lshl_add_u64 v[4:5], s[30:31], 0, v[10:11]
	s_waitcnt vmcnt(2)
	v_mov_b32_e32 v3, v202
	v_mov_b32_e32 v4, v203
	ds_bpermute_b32 v5, v18, v3
	s_waitcnt lgkmcnt(0)
	v_add_f32_e32 v5, v3, v5
	v_cndmask_b32_e64 v3, v5, v3, s[18:19]
	ds_bpermute_b32 v5, v19, v3
	s_waitcnt lgkmcnt(0)
	v_add_f32_e32 v5, v3, v5
	v_cndmask_b32_e64 v3, v5, v3, s[6:7]
	ds_bpermute_b32 v5, v20, v3
	s_waitcnt lgkmcnt(0)
	v_add_f32_e32 v5, v3, v5
	v_cndmask_b32_e64 v3, v5, v3, s[8:9]
	ds_bpermute_b32 v5, v21, v3
	s_waitcnt lgkmcnt(0)
	v_add_f32_e32 v5, v3, v5
	v_cndmask_b32_e64 v3, v5, v3, s[10:11]
	ds_bpermute_b32 v5, v22, v3
	s_waitcnt lgkmcnt(0)
	v_add_f32_e32 v5, v3, v5
	v_cndmask_b32_e64 v5, v5, v3, s[12:13]
	ds_bpermute_b32 v3, v23, v5
	s_waitcnt lgkmcnt(0)
; __device__ __forceinline__ void mlstm_scalar_table_wg(Frame& F, int bh) {
;     ...
;     for (int i = 0; i < 4; ++i) { const int c = 4 * wave + i; const size_t r = (size_t)b * SEQ + (size_t)c * 64 + lane;
;         const float ig = GT[r * 8 + h], lf = GT[r * 8 + 4 + h];
;         float s = lf;
; #pragma unroll
;         for (int o = 1; o < 64; o <<= 1) { const float t = __shfl_up(s, o); if (lane >= o) s += t; }
;         bc[i] = s; as[i] = ig - s; float p = as[i];
; #pragma unroll
;         for (int o = 1; o < 64; o <<= 1) { const float t = __shfl_up(p, o); if (lane >= o) p = fmaxf(p, t); }
;         pm[i] = p;
;         if (lane == 63) { B63[c] = s; P63[c] = p; } }
;     __syncthreads();
	v_add_f32_e32 v3, v5, v3
	v_cndmask_b32_e64 v28, v3, v5, s[14:15]
	v_sub_f32_e32 v27, v4, v28
	ds_bpermute_b32 v4, v18, v27
	s_waitcnt lgkmcnt(0)
	v_max_f32_e32 v4, v4, v4
	v_max_f32_e32 v4, v27, v4
	v_cndmask_b32_e64 v4, v4, v27, s[18:19]
	ds_bpermute_b32 v5, v19, v4
	s_waitcnt lgkmcnt(0)
	v_max_f32_e32 v5, v5, v5
	v_max_f32_e32 v5, v4, v5
	v_cndmask_b32_e64 v4, v5, v4, s[6:7]
	ds_bpermute_b32 v5, v20, v4
	s_waitcnt lgkmcnt(0)
	v_max_f32_e32 v5, v5, v5
	v_max_f32_e32 v5, v4, v5
	v_cndmask_b32_e64 v4, v5, v4, s[8:9]
	ds_bpermute_b32 v5, v21, v4
	s_waitcnt lgkmcnt(0)
	v_max_f32_e32 v5, v5, v5
	v_max_f32_e32 v5, v4, v5
	v_cndmask_b32_e64 v4, v5, v4, s[10:11]
	ds_bpermute_b32 v5, v22, v4
	s_waitcnt lgkmcnt(0)
	v_max_f32_e32 v5, v5, v5
	v_max_f32_e32 v5, v4, v5
	v_cndmask_b32_e64 v34, v5, v4, s[12:13]
	ds_bpermute_b32 v4, v23, v34
	v_max_f32_e32 v5, v34, v34
	s_waitcnt lgkmcnt(0)
	v_max_f32_e32 v4, v4, v4
	v_max_f32_e32 v36, v5, v4
	s_and_saveexec_b64 s[62:63], s[0:1]
	v_mov_b32_e32 v4, s25
	ds_write2_b32 v4, v3, v36 offset0:2 offset1:34
	s_or_b64 exec, exec, s[62:63]
	s_add_u32 s27, s27, s40
	s_addc_u32 s29, s28, s41
	s_add_u32 s28, s27, s60
	s_addc_u32 s29, s29, s61
	v_lshl_add_u64 v[4:5], s[28:29], 0, v[10:11]
	s_waitcnt vmcnt(0)
	v_mov_b32_e32 v3, v204
	v_mov_b32_e32 v4, v205
	ds_bpermute_b32 v5, v18, v3
	s_waitcnt lgkmcnt(0)
	v_add_f32_e32 v5, v3, v5
	v_cndmask_b32_e64 v3, v5, v3, s[18:19]
	ds_bpermute_b32 v5, v19, v3
	s_waitcnt lgkmcnt(0)
	v_add_f32_e32 v5, v3, v5
	v_cndmask_b32_e64 v3, v5, v3, s[6:7]
	ds_bpermute_b32 v5, v20, v3
	s_waitcnt lgkmcnt(0)
	v_add_f32_e32 v5, v3, v5
	v_cndmask_b32_e64 v3, v5, v3, s[8:9]
	ds_bpermute_b32 v5, v21, v3
	s_waitcnt lgkmcnt(0)
	v_add_f32_e32 v5, v3, v5
	v_cndmask_b32_e64 v3, v5, v3, s[10:11]
	ds_bpermute_b32 v5, v22, v3
	s_waitcnt lgkmcnt(0)
	v_add_f32_e32 v5, v3, v5
	v_cndmask_b32_e64 v5, v5, v3, s[12:13]
	ds_bpermute_b32 v3, v23, v5
	s_waitcnt lgkmcnt(0)
	v_add_f32_e32 v3, v5, v3
	v_cndmask_b32_e64 v26, v3, v5, s[14:15]
	v_sub_f32_e32 v25, v4, v26
	ds_bpermute_b32 v4, v18, v25
	s_waitcnt lgkmcnt(0)
	v_max_f32_e32 v4, v4, v4
	v_max_f32_e32 v4, v25, v4
	v_cndmask_b32_e64 v4, v4, v25, s[18:19]
	ds_bpermute_b32 v5, v19, v4
	s_waitcnt lgkmcnt(0)
	v_max_f32_e32 v5, v5, v5
	v_max_f32_e32 v5, v4, v5
	v_cndmask_b32_e64 v4, v5, v4, s[6:7]
	ds_bpermute_b32 v5, v20, v4
	s_waitcnt lgkmcnt(0)
	v_max_f32_e32 v5, v5, v5
	v_max_f32_e32 v5, v4, v5
	v_cndmask_b32_e64 v4, v5, v4, s[8:9]
	ds_bpermute_b32 v5, v21, v4
	s_waitcnt lgkmcnt(0)
	v_max_f32_e32 v5, v5, v5
	v_max_f32_e32 v5, v4, v5
	v_cndmask_b32_e64 v4, v5, v4, s[10:11]
	ds_bpermute_b32 v5, v22, v4
	s_waitcnt lgkmcnt(0)
	v_max_f32_e32 v5, v5, v5
	v_max_f32_e32 v5, v4, v5
	v_cndmask_b32_e64 v29, v5, v4, s[12:13]
	ds_bpermute_b32 v4, v23, v29
	v_max_f32_e32 v5, v29, v29
	s_waitcnt lgkmcnt(0)
	v_max_f32_e32 v4, v4, v4
	v_max_f32_e32 v30, v5, v4
	s_and_saveexec_b64 s[60:61], s[0:1]
	v_mov_b32_e32 v4, s25
	ds_write2_b32 v4, v3, v30 offset0:3 offset1:35
	s_or_b64 exec, exec, s[60:61]
	s_waitcnt lgkmcnt(0)
	s_barrier
	s_and_saveexec_b64 s[60:61], s[16:17]
	s_cbranch_execz .LBB0_701
; __device__ __forceinline__ void mlstm_scalar_table_wg(Frame& F, int bh) {
;     ...
;     if (F.tid == 0) { float m = 0.f;
;         for (int c = 0; c < 32; ++c) { MC[c] = m; const float mm = fmaxf(m, P63[c]); M63[c] = mm; m = B63[c] + mm; } }
	ds_read_b128 v[42:45], v2 offset:128
	ds_read_b128 v[46:49], v2
	ds_read_b128 v[50:53], v2 offset:16
	ds_read_b128 v[54:57], v2 offset:32
	ds_read_b128 v[6:9], v2 offset:48
	s_waitcnt lgkmcnt(4)
	v_max_f32_e32 v3, v42, v42
	v_max_f32_e32 v42, 0, v3
	s_waitcnt lgkmcnt(3)
	v_add_f32_e32 v3, v42, v46
	v_max_f32_e32 v4, v43, v43
	v_max_f32_e32 v43, v3, v4
	v_add_f32_e32 v4, v43, v47
	v_max_f32_e32 v5, v44, v44
	v_max_f32_e32 v44, v4, v5
	v_add_f32_e32 v5, v44, v48
	ds_write_b128 v2, v[2:5] offset:256
	v_max_f32_e32 v3, v45, v45
	v_max_f32_e32 v45, v5, v3
	ds_write_b128 v2, v[42:45] offset:384
	v_add_f32_e32 v42, v45, v49
	ds_read_b128 v[44:47], v2 offset:144
	s_waitcnt lgkmcnt(0)
	v_max_f32_e32 v3, v44, v44
	v_max_f32_e32 v48, v42, v3
	v_add_f32_e32 v43, v48, v50
	v_max_f32_e32 v3, v45, v45
	v_max_f32_e32 v49, v43, v3
	v_add_f32_e32 v44, v49, v51
	v_max_f32_e32 v3, v46, v46
	v_max_f32_e32 v50, v44, v3
	v_add_f32_e32 v45, v50, v52
	v_max_f32_e32 v3, v47, v47
	ds_write_b128 v2, v[42:45] offset:272
	v_max_f32_e32 v51, v45, v3
	ds_read_b128 v[44:47], v2 offset:160
	v_add_f32_e32 v42, v51, v53
	ds_write_b128 v2, v[48:51] offset:400
	s_waitcnt lgkmcnt(1)
	v_max_f32_e32 v3, v44, v44
	v_max_f32_e32 v48, v42, v3
	v_add_f32_e32 v43, v48, v54
	v_max_f32_e32 v3, v45, v45
	v_max_f32_e32 v49, v43, v3
	v_add_f32_e32 v44, v49, v55
	v_max_f32_e32 v3, v46, v46
	v_max_f32_e32 v50, v44, v3
	v_add_f32_e32 v45, v50, v56
	v_max_f32_e32 v3, v47, v47
	ds_write_b128 v2, v[42:45] offset:288
	v_max_f32_e32 v51, v45, v3
	ds_read_b128 v[42:45], v2 offset:176
	v_add_f32_e32 v4, v51, v57
	ds_write_b128 v2, v[48:51] offset:416
	s_waitcnt lgkmcnt(1)
	v_max_f32_e32 v3, v42, v42
	v_max_f32_e32 v42, v4, v3
	v_add_f32_e32 v5, v42, v6
	v_max_f32_e32 v3, v43, v43
	v_max_f32_e32 v43, v5, v3
	v_add_f32_e32 v6, v43, v7
	v_max_f32_e32 v3, v44, v44
	v_max_f32_e32 v44, v6, v3
	v_add_f32_e32 v7, v44, v8
	v_max_f32_e32 v3, v45, v45
	v_max_f32_e32 v45, v7, v3
	ds_write_b128 v2, v[4:7] offset:304
	v_add_f32_e32 v4, v45, v9
	ds_read_b128 v[6:9], v2 offset:192
	ds_write_b128 v2, v[42:45] offset:432
	ds_read_b128 v[44:47], v2 offset:64
	s_waitcnt lgkmcnt(2)
	v_max_f32_e32 v3, v6, v6
	v_max_f32_e32 v42, v4, v3
	s_waitcnt lgkmcnt(0)
	v_add_f32_e32 v5, v42, v44
	v_max_f32_e32 v3, v7, v7
	v_max_f32_e32 v43, v5, v3
	v_add_f32_e32 v6, v43, v45
	v_max_f32_e32 v3, v8, v8
	v_max_f32_e32 v44, v6, v3
	v_add_f32_e32 v7, v44, v46
	v_max_f32_e32 v3, v9, v9
	ds_write_b128 v2, v[4:7] offset:320
	v_max_f32_e32 v45, v7, v3
	ds_read_b128 v[6:9], v2 offset:208
	ds_write_b128 v2, v[42:45] offset:448
	v_add_f32_e32 v4, v45, v47
	ds_read_b128 v[44:47], v2 offset:80
	s_waitcnt lgkmcnt(2)
	v_max_f32_e32 v3, v6, v6
	v_max_f32_e32 v42, v4, v3
	v_max_f32_e32 v3, v7, v7
	s_waitcnt lgkmcnt(0)
	v_add_f32_e32 v5, v42, v44
	v_max_f32_e32 v43, v5, v3
	v_add_f32_e32 v6, v43, v45
	v_max_f32_e32 v3, v8, v8
	v_max_f32_e32 v44, v6, v3
	v_add_f32_e32 v7, v44, v46
	v_max_f32_e32 v3, v9, v9
	ds_write_b128 v2, v[4:7] offset:336
	v_max_f32_e32 v45, v7, v3
	ds_read_b128 v[6:9], v2 offset:224
	ds_write_b128 v2, v[42:45] offset:464
	v_add_f32_e32 v4, v45, v47
	ds_read_b128 v[44:47], v2 offset:96
	s_waitcnt lgkmcnt(2)
	v_max_f32_e32 v3, v6, v6
	v_max_f32_e32 v42, v4, v3
	v_max_f32_e32 v3, v7, v7
	s_waitcnt lgkmcnt(0)
	v_add_f32_e32 v5, v42, v44
	v_max_f32_e32 v43, v5, v3
	v_add_f32_e32 v6, v43, v45
	v_max_f32_e32 v3, v8, v8
	v_max_f32_e32 v44, v6, v3
	v_add_f32_e32 v7, v44, v46
	v_max_f32_e32 v3, v9, v9
	ds_write_b128 v2, v[4:7] offset:352
	v_max_f32_e32 v45, v7, v3
	ds_read_b128 v[6:9], v2 offset:240
	ds_write_b128 v2, v[42:45] offset:480
	v_add_f32_e32 v4, v45, v47
	ds_read_b96 v[44:46], v2 offset:112
	s_waitcnt lgkmcnt(2)
	v_max_f32_e32 v3, v6, v6
	v_max_f32_e32 v42, v4, v3
	v_max_f32_e32 v3, v7, v7
	s_waitcnt lgkmcnt(0)
	v_add_f32_e32 v5, v42, v44
	v_max_f32_e32 v43, v5, v3
	v_add_f32_e32 v6, v43, v45
	v_max_f32_e32 v3, v8, v8
	v_max_f32_e32 v44, v6, v3
	v_add_f32_e32 v7, v44, v46
	v_max_f32_e32 v3, v9, v9
	v_max_f32_e32 v45, v7, v3
	ds_write_b128 v2, v[4:7] offset:368
	ds_write_b128 v2, v[42:45] offset:496
